# attention unit prologues: second K/V tile loads issued with the first tile and Q (one exposed round trip instead of two), MLA and GQA
# speedup vs baseline: 1.0021x; 1.0021x over previous
.LBB0_2477:
	s_lshr_b32 s8, s69, 2
	s_and_b64 s[6:7], s[24:25], exec
	s_cselect_b32 s6, s8, s69
	s_and_b32 s18, s6, 7
	s_lshl_b64 s[6:7], s[40:41], 10
	s_add_u32 s6, s37, s6
	s_addc_u32 s7, s52, s7
	s_lshl_b32 s70, s18, 7
	s_add_u32 s6, s6, s70
	s_addc_u32 s7, s7, 0
	s_lshl_b64 s[8:9], s[40:41], 9
	s_add_u32 s8, s53, s8
	s_addc_u32 s9, s56, s9
	s_lshl_b32 s18, s18, 6
	s_add_u32 s8, s8, s18
	s_addc_u32 s9, s9, 0
	s_lshl_b64 s[42:43], s[4:5], 10
	s_add_u32 s18, s59, s42
	s_addc_u32 s19, s66, s43
	s_add_u32 s48, s18, s70
	v_mov_b32_e32 v197, v0
	s_addc_u32 s49, s19, 0
	s_lshl_b64 s[44:45], s[4:5], 6
	s_add_u32 s46, s57, s44
	v_ashrrev_i32_e32 v47, 1, v197
	v_bfi_b32 v4, s31, v47, v197
	s_addc_u32 s47, s58, s45
	v_ashrrev_i32_e32 v5, 31, v4
	s_add_u32 s4, s67, s42
	s_waitcnt vmcnt(0)
	v_lshlrev_b64 v[6:7], 10, v[4:5]
	v_lshlrev_b64 v[4:5], 9, v[4:5]
	v_ashrrev_i32_e32 v50, 3, v197
	s_addc_u32 s5, s68, s43
	v_lshl_add_u64 v[6:7], s[6:7], 0, v[6:7]
	v_and_b32_e32 v48, 32, v197
	v_mov_b32_e32 v49, v3
	v_lshl_add_u64 v[4:5], s[8:9], 0, v[4:5]
	v_and_b32_e32 v12, 7, v197
	v_ashrrev_i32_e32 v51, 31, v50
	s_add_u32 s50, s4, s70
	v_mov_b32_e32 v196, 0x7f7f7f7f
	v_lshl_add_u64 v[6:7], v[6:7], 0, v[48:49]
	v_lshl_add_u64 v[4:5], v[4:5], 0, v[48:49]
	v_lshlrev_b32_e32 v2, 4, v12
	v_lshlrev_b64 v[44:45], 10, v[50:51]
	s_addc_u32 s51, s5, 0
	global_load_dwordx4 v[120:123], v[6:7], off offset:16
	global_load_dwordx4 v[116:119], v[6:7], off
	global_load_dwordx4 v[112:115], v[6:7], off offset:80
	global_load_dwordx4 v[108:111], v[6:7], off offset:64
	global_load_dwordx4 v[104:107], v[4:5], off offset:16
	global_load_dwordx4 v[100:103], v[4:5], off
	v_or_b32_e32 v4, v44, v2
	v_mov_b32_e32 v5, v45
	v_lshl_add_u64 v[6:7], s[50:51], 0, v[4:5]
	v_lshl_add_u64 v[4:5], s[48:49], 0, v[4:5]
	global_load_dwordx4 v[8:11], v[6:7], off
	s_mov_b32 s100, 0x10000
	s_mov_b32 s101, 0
	v_lshl_add_u64 v[180:181], v[6:7], 0, s[100:101]
	v_lshl_add_u64 v[184:185], v[4:5], 0, s[100:101]
	global_load_dwordx4 v[180:183], v[180:181], off
	global_load_dwordx4 v[184:187], v[184:185], off
	global_load_dwordx4 v[4:7], v[4:5], off
	v_lshlrev_b32_e32 v49, 4, v197
	s_movk_i32 s4, 0xff
	s_movk_i32 s6, 0x100
	v_bfe_u32 v55, v197, 2, 6
	v_and_b32_e32 v46, 48, v49
	v_cmp_lt_i32_e64 s[4:5], s4, v197
	v_cmp_gt_i32_e64 s[6:7], s6, v197
	s_and_saveexec_b64 s[8:9], s[6:7]
	s_cbranch_execz .LBB0_2479
	v_lshl_or_b32 v13, v55, 6, v46
	global_load_dwordx4 v[164:167], v13, s[46:47]
	s_add_u32 s100, s46, 0x1000
	s_addc_u32 s101, s47, 0
	global_load_dwordx4 v[168:171], v13, s[100:101]
.LBB0_2479:
	s_or_b64 exec, exec, s[8:9]
	v_lshrrev_b32_e32 v12, 1, v12
	v_lshrrev_b32_e32 v14, 4, v197
	v_bitop3_b32 v12, v12, v14, 3 bitop3:0x78
	v_lshlrev_b32_e32 v13, 7, v50
	v_lshlrev_b32_e32 v12, 5, v12
	v_and_b32_e32 v14, 16, v49
	v_or3_b32 v12, v12, v14, v13
	v_add_u32_e32 v206, s20, v12
	s_waitcnt vmcnt(0)
	s_waitcnt vmcnt(1)
	ds_write_b128 v206, v[8:11]
	v_and_b32_e32 v8, 0x70, v197
	v_bitop3_b32 v207, v2, v13, v8 bitop3:0xde
	v_add_u32_e32 v208, s20, v207
	v_lshlrev_b32_e32 v52, 6, v55
	v_bitop3_b32 v53, v49, 48, v197 bitop3:0x48
	s_waitcnt vmcnt(0)
	ds_write_b128 v208, v[4:7] offset:24576
	s_and_saveexec_b64 s[8:9], s[6:7]
	v_lshlrev_b32_e32 v4, 6, v55
	v_bitop3_b32 v5, v49, 48, v197 bitop3:0x48
	v_add3_u32 v4, s20, v4, v5
	ds_write_b128 v4, v[164:167] offset:51200
	s_or_b64 exec, exec, s[8:9]
	v_and_b32_e32 v54, 31, v197
	v_lshlrev_b32_e32 v209, 7, v54
	v_lshlrev_b32_e32 v36, 3, v54
	v_or_b32_e32 v64, 16, v48
	v_add_u32_e32 v217, s20, v209
	v_bitop3_b32 v210, v36, v48, s87 bitop3:0x6c
	v_bitop3_b32 v211, v36, v64, s87 bitop3:0x6c
	v_add_u32_e32 v12, v217, v210
	v_add_u32_e32 v16, v217, v211
	s_waitcnt lgkmcnt(0)
	s_barrier
	ds_read_b128 v[8:11], v16 offset:24576
	ds_read_b128 v[4:7], v12 offset:24576
	ds_read_b128 v[12:15], v12 offset:28672
	ds_read_b128 v[16:19], v16 offset:28672
	s_waitcnt lgkmcnt(2)
	v_mfma_scale_f32_32x32x64_f8f6f4 v[20:35], v[4:11], v[116:123], 0, v196, v196 op_sel_hi:[0,0,0]
	v_or_b32_e32 v37, 64, v48
	v_bitop3_b32 v216, v36, v37, s87 bitop3:0x6c
	v_or_b32_e32 v37, 0x50, v48
	v_bitop3_b32 v218, v36, v37, s87 bitop3:0x6c
	v_add_u32_e32 v56, v217, v216
	v_add_u32_e32 v60, v217, v218
	ds_read_b128 v[40:43], v60 offset:24576
	ds_read_b128 v[36:39], v56 offset:24576
	ds_read_b128 v[56:59], v56 offset:28672
	ds_read_b128 v[60:63], v60 offset:28672
	v_lshlrev_b32_e32 v219, 6, v54
	v_add_u32_e32 v222, s20, v219
	s_mov_b64 s[8:9], 0x10000
	s_waitcnt lgkmcnt(4)
	v_mfma_scale_f32_32x32x64_f8f6f4 v[4:19], v[12:19], v[116:123], 0, v196, v196 op_sel_hi:[0,0,0]
	s_waitcnt lgkmcnt(2)
	v_mfma_scale_f32_32x32x64_f8f6f4 v[20:35], v[36:43], v[108:115], v[20:35], v196, v196 op_sel_hi:[0,0,0]
	v_lshlrev_b32_e32 v36, 2, v54
	v_bitop3_b32 v220, v36, v48, 48 bitop3:0x6c
	v_bitop3_b32 v221, v36, v64, 48 bitop3:0x6c
	v_add_u32_e32 v40, v222, v220
	v_lshlrev_b64 v[64:65], 10, v[50:51]
	v_or_b32_e32 v64, v64, v2
	v_lshl_add_u64 v[64:65], v[64:65], 0, s[8:9]
	v_lshl_add_u64 v[66:67], s[50:51], 0, v[64:65]
	v_lshl_add_u64 v[64:65], s[48:49], 0, v[64:65]
	s_waitcnt lgkmcnt(0)
	v_mfma_scale_f32_32x32x64_f8f6f4 v[4:19], v[56:63], v[108:115], v[4:19], v196, v196 op_sel_hi:[0,0,0]
	v_add_u32_e32 v60, v222, v221
	ds_read_b128 v[36:39], v40 offset:51200
	ds_read_b128 v[56:59], v40 offset:53248
	ds_read_b128 v[40:43], v60 offset:51200
	ds_read_b128 v[60:63], v60 offset:53248
	s_waitcnt lgkmcnt(1)
	v_mfma_scale_f32_32x32x64_f8f6f4 v[20:35], v[36:43], v[100:107], v[20:35], v196, v196 op_sel_hi:[0,0,0]
	s_waitcnt lgkmcnt(0)
	v_mfma_scale_f32_32x32x64_f8f6f4 v[4:19], v[56:63], v[100:107], v[4:19], v196, v196 op_sel_hi:[0,0,0]
	s_nop 15
	v_max_f32_e32 v64, v21, v21
	v_max_f32_e32 v65, v20, v20
	v_max_f32_e32 v64, v65, v64
	v_max3_f32 v64, v64, v22, v23
	v_max3_f32 v64, v64, v24, v25
	v_max3_f32 v64, v64, v26, v27
	v_max3_f32 v64, v64, v28, v29
	v_max3_f32 v64, v64, v30, v31
	v_max3_f32 v64, v64, v32, v33
	v_max3_f32 v64, v64, v34, v35
	v_max3_f32 v56, v64, v4, v5
	v_max3_f32 v56, v56, v6, v7
	v_max3_f32 v56, v56, v8, v9
	v_max3_f32 v56, v56, v10, v11
	v_max3_f32 v56, v56, v12, v13
	v_max3_f32 v56, v56, v14, v15
	v_max3_f32 v56, v56, v16, v17
	v_max3_f32 v56, v56, v18, v19
	v_mov_b32_e32 v57, v56
	s_nop 1
	v_permlane32_swap_b32_e32 v56, v57
	v_max_f32_e32 v57, v57, v57
	v_max_f32_e32 v56, v56, v56
	v_max_f32_e32 v56, v56, v57
	v_add_f32_e32 v57, 0x7149f2ca, v56
	v_cmp_ge_f32_e32 vcc, s80, v57
	s_cmp_eq_u64 vcc, exec
	s_cselect_b64 s[8:9], -1, 0
	s_and_saveexec_b64 s[18:19], s[4:5]
	s_xor_b64 s[18:19], exec, s[18:19]
	v_lshlrev_b32_e32 v52, 6, v55
	s_or_saveexec_b64 s[18:19], s[18:19]
	s_xor_b64 exec, exec, s[18:19]
	s_cbranch_execz .LBB0_2485
	v_or_b32_e32 v58, v52, v46
	v_mov_b32_e32 v59, v3
	v_lshl_add_u64 v[58:59], s[46:47], 0, v[58:59]
	v_add_co_u32_e32 v58, vcc, 0x1000, v58
	s_nop 1
	v_addc_co_u32_e32 v59, vcc, 0, v59, vcc

.LBB0_2487:
	s_or_b64 exec, exec, s[18:19]
	ds_write_b128 v206, v[180:183] offset:8192
	ds_write_b128 v208, v[184:187] offset:32768
	s_and_saveexec_b64 s[18:19], s[4:5]
	s_xor_b64 s[4:5], exec, s[18:19]
	v_bitop3_b32 v53, v49, 48, v197 bitop3:0x48
	s_andn2_saveexec_b64 s[4:5], s[4:5]
	v_add3_u32 v36, s20, v52, v53
	ds_write_b128 v36, v[168:171] offset:55296
	s_or_b64 exec, exec, s[4:5]
	v_max_f32_e32 v37, 0xf149f2ca, v56
	v_cndmask_b32_e64 v223, v37, v248, s[8:9]
	v_mul_f32_e32 v36, 0xbdd53b94, v223
	v_fmamk_f32 v20, v20, 0x3dd53b94, v36
	v_exp_f32_e32 v239, v20
	v_sub_f32_e32 v20, 0xf149f2ca, v37
	v_mul_f32_e32 v20, 0x3dd53b94, v20
	v_exp_f32_e32 v20, v20
	v_pk_fma_f32 v[84:85], v[6:7], s[86:87], v[36:37] op_sel_hi:[1,0,0]
	v_pk_fma_f32 v[86:87], v[4:5], s[86:87], v[36:37] op_sel_hi:[1,0,0]
	v_lshrrev_b32_e32 v5, 1, v197
	v_lshlrev_b32_e32 v7, 3, v197
	v_pk_fma_f32 v[182:183], v[8:9], s[86:87], v[36:37] op_sel_hi:[1,0,0]
	v_and_b32_e32 v6, 16, v197
	v_and_or_b32 v5, v5, 7, v48
	v_and_b32_e32 v9, 8, v7
	v_pk_fma_f32 v[180:181], v[10:11], s[86:87], v[36:37] op_sel_hi:[1,0,0]
	v_lshlrev_b32_e32 v5, 7, v5
	v_and_b32_e32 v8, 0x60, v7
	v_add3_u32 v10, v6, s20, v9
	v_and_b32_e32 v4, 0x3fffffc0, v197
	v_add3_u32 v201, v10, v5, v8
	v_or3_b32 v5, v9, v6, v5
	v_cndmask_b32_e64 v224, v20, 1.0, s[8:9]
	v_lshl_add_u32 v189, v4, 2, s20
	v_and_b32_e32 v4, 63, v197
	v_or_b32_e32 v6, v5, v8
	v_bitop3_b32 v5, v5, s30, v7 bitop3:0x34
	s_add_u32 s8, s94, s44
	v_add_u32_e32 v204, s20, v5
	v_cmp_gt_u32_e64 s[4:5], 32, v4
	s_addc_u32 s9, s95, s45
	v_and_b32_e32 v4, 0xfc0, v49
	v_mov_b32_e32 v5, v3
	v_lshl_add_u64 v[4:5], s[8:9], 0, v[4:5]
	s_add_u32 s8, s70, s42
	v_and_b32_e32 v188, 0xffffffe0, v47
	v_fmamk_f32 v21, v21, 0x3dd53b94, v36
	v_fmamk_f32 v22, v22, 0x3dd53b94, v36
	v_fmamk_f32 v23, v23, 0x3dd53b94, v36
	v_fmamk_f32 v24, v24, 0x3dd53b94, v36
	v_fmamk_f32 v25, v25, 0x3dd53b94, v36
	v_fmamk_f32 v26, v26, 0x3dd53b94, v36
	v_fmamk_f32 v27, v27, 0x3dd53b94, v36
	v_fmamk_f32 v28, v28, 0x3dd53b94, v36
	v_fmamk_f32 v29, v29, 0x3dd53b94, v36
	v_fmamk_f32 v30, v30, 0x3dd53b94, v36
	v_fmamk_f32 v31, v31, 0x3dd53b94, v36
	v_fmamk_f32 v32, v32, 0x3dd53b94, v36
	v_fmamk_f32 v33, v33, 0x3dd53b94, v36
	v_fmamk_f32 v34, v34, 0x3dd53b94, v36
	v_fmamk_f32 v35, v35, 0x3dd53b94, v36
	v_mov_b32_e32 v47, v3
	s_addc_u32 s9, 0, s43
	v_exp_f32_e32 v240, v21
	v_exp_f32_e32 v231, v22
	v_exp_f32_e32 v232, v23
	v_exp_f32_e32 v235, v24
	v_exp_f32_e32 v236, v25
	v_exp_f32_e32 v233, v26
	v_exp_f32_e32 v234, v27
	v_exp_f32_e32 v229, v28
	v_exp_f32_e32 v230, v29
	v_exp_f32_e32 v184, v30
	v_exp_f32_e32 v185, v31
	v_exp_f32_e32 v194, v32
	v_exp_f32_e32 v195, v33
	v_exp_f32_e32 v186, v34
	v_exp_f32_e32 v187, v35
	v_pk_fma_f32 v[126:127], v[16:17], s[86:87], v[36:37] op_sel_hi:[1,0,0]
	v_lshl_add_u64 v[190:191], v[4:5], 0, v[46:47]
	v_lshl_add_u64 v[4:5], s[8:9], 0, v[44:45]
	v_mov_b32_e32 v16, v3
	v_mov_b32_e32 v17, v3
	v_pk_fma_f32 v[124:125], v[18:19], s[86:87], v[36:37] op_sel_hi:[1,0,0]
	v_pk_fma_f32 v[128:129], v[14:15], s[86:87], v[36:37] op_sel_hi:[1,0,0]
	v_pk_fma_f32 v[130:131], v[12:13], s[86:87], v[36:37] op_sel_hi:[1,0,0]
	v_xad_u32 v202, v6, 32, s20
	v_xad_u32 v203, v6, 64, s20
	v_add3_u32 v225, s20, v52, v53
	v_lshl_add_u32 v200, v54, 2, v189
	v_lshl_add_u64 v[192:193], v[4:5], 0, v[2:3]
	v_mov_b32_e32 v2, v3
	v_mov_b32_e32 v4, v3
	v_mov_b32_e32 v5, v3
	v_mov_b32_e32 v6, v3
	v_mov_b32_e32 v7, v3
	v_mov_b32_e32 v8, v3
	v_mov_b32_e32 v9, v3
	v_mov_b32_e32 v10, v3
	v_mov_b32_e32 v11, v3
	v_mov_b32_e32 v12, v3
	v_mov_b32_e32 v13, v3
	v_mov_b32_e32 v14, v3
	v_mov_b32_e32 v15, v3
	v_mov_b64_e32 v[66:67], v[16:17]
	v_mov_b64_e32 v[50:51], v[16:17]
	v_mov_b64_e32 v[34:35], v[16:17]
	v_bfe_u32 v198, v197, 5, 1
	v_mov_b64_e32 v[64:65], v[14:15]
	v_mov_b64_e32 v[62:63], v[12:13]
	v_mov_b64_e32 v[60:61], v[10:11]
	v_mov_b64_e32 v[58:59], v[8:9]
	v_mov_b64_e32 v[56:57], v[6:7]
	v_mov_b64_e32 v[54:55], v[4:5]
	v_mov_b64_e32 v[52:53], v[2:3]
	v_mov_b64_e32 v[48:49], v[14:15]
	v_mov_b64_e32 v[46:47], v[12:13]
	v_mov_b64_e32 v[44:45], v[10:11]
	v_mov_b64_e32 v[42:43], v[8:9]
	v_mov_b64_e32 v[40:41], v[6:7]
	v_mov_b64_e32 v[38:39], v[4:5]
	v_mov_b64_e32 v[36:37], v[2:3]
	v_mov_b64_e32 v[32:33], v[14:15]
	v_mov_b64_e32 v[30:31], v[12:13]
	v_mov_b64_e32 v[28:29], v[10:11]
	v_mov_b64_e32 v[26:27], v[8:9]
	v_mov_b64_e32 v[24:25], v[6:7]
	v_mov_b64_e32 v[22:23], v[4:5]
	v_mov_b64_e32 v[20:21], v[2:3]
	v_mov_b64_e32 v[18:19], v[16:17]
	s_mov_b32 s46, 1
	v_lshlrev_b32_e32 v199, 4, v198
	v_mov_b32_e32 v205, 0
	v_mov_b64_e32 v[16:17], v[14:15]
	v_mov_b64_e32 v[14:15], v[12:13]
	v_mov_b64_e32 v[12:13], v[10:11]
	v_mov_b64_e32 v[10:11], v[8:9]
	v_mov_b64_e32 v[8:9], v[6:7]
	v_mov_b64_e32 v[6:7], v[4:5]
	v_mov_b64_e32 v[4:5], v[2:3]
	s_mov_b32 s44, 1
	s_waitcnt lgkmcnt(0)
	s_barrier

.LBB0_2659:
	s_lshr_b32 s18, s68, 2
	s_and_b64 s[6:7], s[8:9], exec
	s_cselect_b32 s18, s18, s68
	s_and_b32 s19, s18, 7
	s_lshl_b64 s[6:7], s[24:25], 10
	s_add_u32 s6, s52, s6
	s_addc_u32 s7, s53, s7
	s_lshl_b32 s69, s19, 7
	s_add_u32 s38, s6, s69
	s_addc_u32 s39, s7, 0
	s_lshl_b64 s[6:7], s[4:5], 8
	s_add_u32 s4, s56, s6
	s_addc_u32 s5, s57, s7
	s_lshl_b32 s18, s18, 5
	s_and_b32 s18, s18, 0x80
	s_add_u32 s4, s4, s18
	s_addc_u32 s5, s5, 0
	v_mov_b32_e32 v163, v0
	s_add_u32 s19, s58, s6
	s_addc_u32 s35, s59, s7
	v_ashrrev_i32_e32 v14, 3, v163
	v_and_b32_e32 v2, 7, v163
	v_ashrrev_i32_e32 v15, 31, v14
	s_add_u32 s34, s19, s18
	v_lshlrev_b32_e32 v2, 4, v2
	v_lshlrev_b64 v[52:53], 8, v[14:15]
	s_addc_u32 s35, s35, 0
	v_or_b32_e32 v54, v52, v2
	v_mov_b32_e32 v55, v53
	v_mov_b32_e32 v162, 0x7f7f7f7f
	v_lshl_add_u64 v[4:5], s[34:35], 0, v[54:55]
	v_lshl_add_u64 v[10:11], s[4:5], 0, v[54:55]
	s_mov_b32 s100, 0x4000
	s_mov_b32 s101, 0
	v_lshl_add_u64 v[64:65], v[4:5], 0, s[100:101]
	v_lshl_add_u64 v[68:69], v[10:11], 0, s[100:101]
	global_load_dwordx4 v[6:9], v[4:5], off
	s_nop 0
	global_load_dwordx4 v[10:13], v[10:11], off
	global_load_dwordx4 v[64:67], v[64:65], off
	global_load_dwordx4 v[68:71], v[68:69], off
	v_ashrrev_i32_e32 v15, 1, v163
	v_bfi_b32 v4, s31, v15, v163
	v_ashrrev_i32_e32 v5, 31, v4
	v_lshlrev_b64 v[4:5], 10, v[4:5]
	v_lshl_add_u64 v[16:17], s[38:39], 0, v[4:5]
	v_and_b32_e32 v4, 32, v163
	v_mov_b32_e32 v5, v3
	v_lshl_add_u64 v[16:17], v[16:17], 0, v[4:5]
	global_load_dwordx4 v[112:115], v[16:17], off offset:16
	global_load_dwordx4 v[108:111], v[16:17], off
	global_load_dwordx4 v[104:107], v[16:17], off offset:80
	global_load_dwordx4 v[100:103], v[16:17], off offset:64
	v_bfe_u32 v5, v163, 1, 2
	v_lshrrev_b32_e32 v17, 4, v163
	v_and_b32_e32 v74, 31, v163
	v_lshlrev_b32_e32 v18, 4, v163
	v_bitop3_b32 v5, v5, v17, 3 bitop3:0x78
	v_lshlrev_b32_e32 v16, 3, v163
	v_lshlrev_b32_e32 v14, 7, v14
	v_and_b32_e32 v17, 16, v18
	v_lshlrev_b32_e32 v172, 7, v74
	v_lshlrev_b32_e32 v5, 5, v5
	v_and_b32_e32 v19, 0x70, v163
	v_bitop3_b32 v173, v16, v4, s87 bitop3:0x6c
	v_or_b32_e32 v18, 16, v4
	v_add_u32_e32 v176, s20, v172
	v_or3_b32 v5, v5, v17, v14
	v_bitop3_b32 v175, v2, v14, v19 bitop3:0xde
	v_bitop3_b32 v174, v16, v18, s87 bitop3:0x6c
	v_add_u32_e32 v14, v176, v173
	v_add_u32_e32 v178, s20, v5
	v_add_u32_e32 v177, s20, v175
	v_add_u32_e32 v17, v176, v174
	s_waitcnt vmcnt(0)
	v_and_b32_e32 v5, 0x3fffffc0, v163
	s_mov_b64 s[46:47], 0x4000
	v_lshl_add_u32 v157, v5, 2, s20
	v_and_b32_e32 v156, 0xffffffe0, v15
	s_mov_b32 s37, s36
	s_mov_b32 s38, s36
	s_mov_b32 s39, s36
	s_mov_b32 s40, s36
	s_mov_b32 s41, s36
	s_mov_b32 s42, s36
	s_mov_b32 s43, s36
	s_mov_b32 s44, s36
	s_mov_b32 s45, s36
	s_mov_b32 s48, s36
	s_mov_b32 s49, s36
	s_mov_b32 s50, s36
	s_mov_b32 s51, s36
	v_and_b32_e32 v75, 63, v163
	v_bfe_u32 v164, v163, 5, 1
	v_lshl_add_u32 v170, v74, 2, v157
	v_lshlrev_b32_e32 v169, 4, v164
	v_mov_b32_e32 v171, 0
	s_waitcnt vmcnt(0)
	ds_write_b128 v178, v[6:9]
	ds_write_b128 v177, v[10:13] offset:24576
	s_waitcnt lgkmcnt(0)
	s_barrier
	ds_read_b128 v[6:9], v14 offset:24576
	ds_read_b128 v[10:13], v17 offset:24576
	s_waitcnt lgkmcnt(0)
	v_mfma_scale_f32_32x32x64_f8f6f4 v[20:35], v[6:13], v[108:115], 0, v162, v162 op_sel_hi:[0,0,0]
	v_lshrrev_b32_e32 v6, 1, v163
	v_and_or_b32 v5, v6, 7, v4
	v_lshl_add_u64 v[6:7], v[54:55], 0, s[46:47]
	v_lshl_add_u64 v[8:9], s[4:5], 0, v[6:7]
	v_lshl_add_u64 v[6:7], s[34:35], 0, v[6:7]
	ds_read_b128 v[36:39], v14 offset:28672
	ds_read_b128 v[40:43], v17 offset:28672
	v_or_b32_e32 v6, 64, v4
	v_or_b32_e32 v4, 0x50, v4
	v_bitop3_b32 v180, v16, v6, s87 bitop3:0x6c
	v_lshl_add_u64 v[54:55], v[54:55], 0, s[60:61]
	v_bitop3_b32 v179, v16, v4, s87 bitop3:0x6c
	v_add_u32_e32 v18, v176, v180
	v_lshl_add_u64 v[72:73], s[4:5], 0, v[54:55]
	v_lshlrev_b32_e32 v15, 7, v5
	v_add_u32_e32 v19, v176, v179
	ds_read_b128 v[4:7], v18 offset:24576
	ds_read_b128 v[8:11], v19 offset:24576
	ds_read_b128 v[56:59], v18 offset:28672
	ds_read_b128 v[60:63], v19 offset:28672
	v_lshl_add_u64 v[54:55], s[34:35], 0, v[54:55]
	global_load_dwordx4 v[144:147], v[72:73], off
	global_load_dwordx4 v[140:143], v[54:55], off
	s_waitcnt lgkmcnt(4)
	v_mfma_scale_f32_32x32x64_f8f6f4 v[36:51], v[36:43], v[108:115], 0, v162, v162 op_sel_hi:[0,0,0]
	v_and_b32_e32 v12, 16, v163
	v_and_b32_e32 v14, 8, v16
	v_and_b32_e32 v13, 0x60, v16
	v_add3_u32 v17, v12, s20, v14
	v_or3_b32 v12, v14, v12, v15
	v_add3_u32 v165, v17, v15, v13
	v_or_b32_e32 v13, v12, v13
	v_bitop3_b32 v12, v12, s30, v16 bitop3:0x34
	v_xad_u32 v166, v13, 32, s20
	v_xad_u32 v167, v13, 64, s20
	v_add_u32_e32 v168, s20, v12
	s_mov_b32 s46, s36
	s_mov_b32 s47, s36
	s_waitcnt vmcnt(2)
	v_cmp_gt_u32_e64 s[4:5], 32, v75
	s_waitcnt lgkmcnt(2)
	v_mfma_scale_f32_32x32x64_f8f6f4 v[20:35], v[4:11], v[100:107], v[20:35], v162, v162 op_sel_hi:[0,0,0]
	v_mov_b64_e32 v[4:5], s[36:37]
	v_mov_b64_e32 v[18:19], s[50:51]
	v_mov_b64_e32 v[6:7], s[38:39]
	v_mov_b64_e32 v[8:9], s[40:41]
	v_mov_b64_e32 v[10:11], s[42:43]
	v_mov_b64_e32 v[12:13], s[44:45]
	v_mov_b64_e32 v[14:15], s[46:47]
	v_mov_b64_e32 v[16:17], s[48:49]
	s_mov_b32 s37, 1
	s_waitcnt vmcnt(3)
	ds_write_b128 v178, v[64:67] offset:8192
	s_waitcnt vmcnt(2)
	ds_write_b128 v177, v[68:71] offset:32768
	s_waitcnt lgkmcnt(2)
	v_mfma_scale_f32_32x32x64_f8f6f4 v[36:51], v[56:63], v[100:107], v[36:51], v162, v162 op_sel_hi:[0,0,0]
	s_nop 4
	v_max_f32_e32 v54, v21, v21
	v_max_f32_e32 v55, v20, v20
	v_max_f32_e32 v54, v55, v54
	v_max3_f32 v54, v54, v22, v23
	v_max3_f32 v54, v54, v24, v25
	v_max3_f32 v54, v54, v26, v27
	v_max3_f32 v54, v54, v28, v29
	v_max3_f32 v54, v54, v30, v31
	v_max3_f32 v54, v54, v32, v33
	v_max3_f32 v54, v54, v34, v35
	s_waitcnt lgkmcnt(0)
	s_barrier
	s_nop 2
	v_max3_f32 v54, v54, v36, v37
	v_max3_f32 v54, v54, v38, v39
	v_max3_f32 v54, v54, v40, v41
	v_max3_f32 v54, v54, v42, v43
	v_max3_f32 v54, v54, v44, v45
	v_max3_f32 v54, v54, v46, v47
	v_max3_f32 v54, v54, v48, v49
	v_max3_f32 v54, v54, v50, v51
	v_mov_b32_e32 v55, v54
	s_nop 1
	v_permlane32_swap_b32_e32 v54, v55
	v_max_f32_e32 v55, v55, v55
	v_max_f32_e32 v54, v54, v54
	v_max_f32_e32 v54, v54, v55
	v_add_f32_e32 v55, 0x7149f2ca, v54
	v_cmp_ge_f32_e32 vcc, s81, v55
	s_cmp_eq_u64 vcc, exec
	v_max_f32_e32 v56, 0xf149f2ca, v54
	s_cselect_b64 vcc, -1, 0
	v_cndmask_b32_e32 v132, v56, v248, vcc
	v_mul_f32_e32 v54, 0xbe0293ee, v132
	v_fmamk_f32 v20, v20, 0x3e0293ee, v54
	v_exp_f32_e32 v154, v20
	v_fmamk_f32 v20, v22, 0x3e0293ee, v54
	v_exp_f32_e32 v160, v20
	v_fmamk_f32 v20, v23, 0x3e0293ee, v54
	v_exp_f32_e32 v161, v20
	v_fmamk_f32 v20, v24, 0x3e0293ee, v54
	v_exp_f32_e32 v150, v20
	v_fmamk_f32 v20, v25, 0x3e0293ee, v54
	v_exp_f32_e32 v151, v20
	v_fmamk_f32 v20, v26, 0x3e0293ee, v54
	v_exp_f32_e32 v152, v20
	v_fmamk_f32 v20, v27, 0x3e0293ee, v54
	v_exp_f32_e32 v153, v20
	v_fmamk_f32 v20, v28, 0x3e0293ee, v54
	v_exp_f32_e32 v138, v20
	v_fmamk_f32 v20, v29, 0x3e0293ee, v54
	v_exp_f32_e32 v139, v20
	v_fmamk_f32 v20, v30, 0x3e0293ee, v54
	v_exp_f32_e32 v148, v20
	v_fmamk_f32 v20, v31, 0x3e0293ee, v54
	v_exp_f32_e32 v149, v20
	v_fmamk_f32 v20, v32, 0x3e0293ee, v54
	v_exp_f32_e32 v134, v20
	v_fmamk_f32 v20, v33, 0x3e0293ee, v54
	v_exp_f32_e32 v135, v20
	v_fmamk_f32 v20, v34, 0x3e0293ee, v54
	v_exp_f32_e32 v136, v20
	v_fmamk_f32 v20, v35, 0x3e0293ee, v54
	v_exp_f32_e32 v137, v20
	v_sub_f32_e32 v20, 0xf149f2ca, v56
	v_mul_f32_e32 v20, 0x3e0293ee, v20
	v_exp_f32_e32 v20, v20
	s_add_u32 s18, s66, s18
	v_fmamk_f32 v21, v21, 0x3e0293ee, v54
	s_addc_u32 s19, s67, 0
	v_exp_f32_e32 v155, v21
	s_add_u32 s6, s18, s6
	s_addc_u32 s7, s19, s7
	v_pk_fma_f32 v[116:117], v[50:51], s[72:73], v[54:55] op_sel_hi:[1,0,0]
	v_pk_fma_f32 v[118:119], v[48:49], s[72:73], v[54:55] op_sel_hi:[1,0,0]
	v_pk_fma_f32 v[120:121], v[46:47], s[72:73], v[54:55] op_sel_hi:[1,0,0]
	v_pk_fma_f32 v[122:123], v[44:45], s[72:73], v[54:55] op_sel_hi:[1,0,0]
	v_pk_fma_f32 v[124:125], v[42:43], s[72:73], v[54:55] op_sel_hi:[1,0,0]
	v_pk_fma_f32 v[126:127], v[40:41], s[72:73], v[54:55] op_sel_hi:[1,0,0]
	v_pk_fma_f32 v[128:129], v[38:39], s[72:73], v[54:55] op_sel_hi:[1,0,0]
	v_pk_fma_f32 v[130:131], v[36:37], s[72:73], v[54:55] op_sel_hi:[1,0,0]
	v_cndmask_b32_e64 v181, v20, 1.0, vcc
	v_lshl_add_u64 v[158:159], s[6:7], 0, v[52:53]
	v_mov_b64_e32 v[66:67], v[18:19]
	v_mov_b64_e32 v[50:51], v[18:19]
	v_mov_b64_e32 v[34:35], v[18:19]
	v_mov_b64_e32 v[64:65], v[16:17]
	v_mov_b64_e32 v[62:63], v[14:15]
	v_mov_b64_e32 v[60:61], v[12:13]
	v_mov_b64_e32 v[58:59], v[10:11]
	v_mov_b64_e32 v[56:57], v[8:9]
	v_mov_b64_e32 v[54:55], v[6:7]
	v_mov_b64_e32 v[52:53], v[4:5]
	v_mov_b64_e32 v[48:49], v[16:17]
	v_mov_b64_e32 v[46:47], v[14:15]
	v_mov_b64_e32 v[44:45], v[12:13]
	v_mov_b64_e32 v[42:43], v[10:11]
	v_mov_b64_e32 v[40:41], v[8:9]
	v_mov_b64_e32 v[38:39], v[6:7]
	v_mov_b64_e32 v[36:37], v[4:5]
	v_mov_b64_e32 v[32:33], v[16:17]
	v_mov_b64_e32 v[30:31], v[14:15]
	v_mov_b64_e32 v[28:29], v[12:13]
	v_mov_b64_e32 v[26:27], v[10:11]
	v_mov_b64_e32 v[24:25], v[8:9]
	v_mov_b64_e32 v[22:23], v[6:7]
	v_mov_b64_e32 v[20:21], v[4:5]
